# v62 + one shared copy of the barrier leader's code (entered with a seam number, returns through a compare chain)
# speedup vs baseline: 1.0030x; 1.0006x over previous
; #define LAS __attribute__((address_space(3)))
; DI void grid_bar(unsigned* bar, volatile LAS unsigned* st, int wid) {
;     asm volatile("s_waitcnt vmcnt(0)" ::: "memory");
;     __syncthreads();
;     if (wid == 0) {
.LBB0_241:
	s_cmp_gt_i32 s35, 1
	s_cselect_b64 s[2:3], -1, 0
	s_and_b64 s[4:5], s[36:37], s[2:3]
	s_andn2_b64 vcc, exec, s[4:5]
	s_cbranch_vccnz .LBB0_297
	s_mov_b64 s[8:9], s[0:1]
	s_waitcnt vmcnt(0)
	s_cmp_gt_u32 s88, 63
	s_barrier
	s_cbranch_scc1 .Lbi_0
	s_mov_b32 s99, 0
	s_branch .Lbs_entry
.Lbs_ret_0:
	s_branch .LBB0_296
.Lbi_0:
	s_cmp_gt_u32 s88, 127
	s_cbranch_scc1 .LBB0_296
	buffer_inv sc1
	s_waitcnt vmcnt(0)

; #define LAS __attribute__((address_space(3)))
; DI void grid_bar(unsigned* bar, volatile LAS unsigned* st, int wid) {
;     asm volatile("s_waitcnt vmcnt(0)" ::: "memory");
;     __syncthreads();
;     if (wid == 0) {
.Lconv_skip_0:
	s_cmp_gt_i32 s35, 2
	s_cselect_b64 s[2:3], -1, 0
	s_and_b64 s[4:5], s[8:9], s[2:3]
	s_andn2_b64 vcc, exec, s[4:5]
	s_cbranch_vccnz .LBB0_454
	s_mov_b64 s[8:9], s[0:1]
	s_waitcnt vmcnt(0)
	s_cmp_gt_u32 s88, 63
	s_waitcnt vmcnt(0) lgkmcnt(0)
	s_barrier
	s_cbranch_scc1 .Lbi_1
	s_mov_b32 s99, 1
	s_branch .Lbs_entry
.Lbs_ret_1:
	s_branch .LBB0_453
.Lbi_1:
	s_cmp_gt_u32 s88, 127
	s_cbranch_scc1 .LBB0_453
	buffer_inv sc1
	s_waitcnt vmcnt(0)

; #define LAS __attribute__((address_space(3)))
; DI void grid_bar(unsigned* bar, volatile LAS unsigned* st, int wid) {
;     asm volatile("s_waitcnt vmcnt(0)" ::: "memory");
;     __syncthreads();
;     if (wid == 0) {
.LBB0_471:
	s_cmp_gt_i32 s35, 3
	s_cselect_b64 s[2:3], -1, 0
	s_and_b64 s[4:5], s[16:17], s[2:3]
	s_andn2_b64 vcc, exec, s[4:5]
	s_cbranch_vccnz .LBB0_527
	s_mov_b64 s[8:9], s[0:1]
	s_waitcnt vmcnt(0)
	s_cmp_gt_u32 s88, 63
	s_waitcnt vmcnt(0) lgkmcnt(0)
	s_barrier
	s_cbranch_scc1 .Lbi_2
	s_mov_b32 s99, 2
	s_branch .Lbs_entry
.Lbs_ret_2:
	s_branch .LBB0_526
.Lbi_2:
	s_cmp_gt_u32 s88, 127
	s_cbranch_scc1 .LBB0_526
	buffer_inv sc1
	s_waitcnt vmcnt(0)

; #define LAS __attribute__((address_space(3)))
; DI void grid_bar(unsigned* bar, volatile LAS unsigned* st, int wid) {
;     asm volatile("s_waitcnt vmcnt(0)" ::: "memory");
;     __syncthreads();
;     if (wid == 0) {
.Lp2_skip:
	s_cmp_gt_i32 s35, 4
	s_cselect_b64 s[2:3], -1, 0
	s_and_b64 s[4:5], s[4:5], s[2:3]
	s_andn2_b64 vcc, exec, s[4:5]
	s_cbranch_vccnz .LBB0_602
	s_mov_b64 s[8:9], s[0:1]
	s_waitcnt vmcnt(0)
	s_cmp_gt_u32 s88, 63
	s_waitcnt vmcnt(0) lgkmcnt(0)
	s_barrier
	s_cbranch_scc1 .Lbi_3
	s_mov_b32 s99, 3
	s_branch .Lbs_entry
.Lbs_ret_3:
	s_branch .LBB0_601
.Lbi_3:
	s_cmp_gt_u32 s88, 127
	s_cbranch_scc1 .LBB0_601
	buffer_inv sc1
	s_waitcnt vmcnt(0)

; #define LAS __attribute__((address_space(3)))
; DI void grid_bar(unsigned* bar, volatile LAS unsigned* st, int wid) {
;     asm volatile("s_waitcnt vmcnt(0)" ::: "memory");
;     __syncthreads();
;     if (wid == 0) {
.LBB0_641:
	s_cmp_gt_i32 s35, 5
	s_cselect_b64 s[2:3], -1, 0
	s_and_b64 s[4:5], s[8:9], s[2:3]
	s_andn2_b64 vcc, exec, s[4:5]
	s_cbranch_vccnz .LBB0_697
	s_mov_b64 s[8:9], s[0:1]
	s_waitcnt vmcnt(0)
	s_cmp_gt_u32 s88, 63
	s_waitcnt vmcnt(0) lgkmcnt(0)
	s_barrier
	s_cbranch_scc1 .Lbi_4
	s_mov_b32 s99, 4
	s_branch .Lbs_entry
.Lbs_ret_4:
	s_branch .LBB0_696
.Lbi_4:
	s_cmp_gt_u32 s88, 127
	s_cbranch_scc1 .LBB0_696
	buffer_inv sc1
	s_waitcnt vmcnt(0)

; #define LAS __attribute__((address_space(3)))
; DI void grid_bar(unsigned* bar, volatile LAS unsigned* st, int wid) {
;     asm volatile("s_waitcnt vmcnt(0)" ::: "memory");
;     __syncthreads();
;     if (wid == 0) {
.Lconv_tramp_skip:
	s_cmp_gt_i32 s35, 6
	s_cselect_b64 s[2:3], -1, 0
	s_and_b64 s[4:5], s[4:5], s[2:3]
	s_andn2_b64 vcc, exec, s[4:5]
	s_cbranch_vccnz .LBB0_766
	s_mov_b64 s[8:9], s[0:1]
	s_waitcnt vmcnt(0)
	s_cmp_gt_u32 s88, 63
	s_waitcnt vmcnt(0) lgkmcnt(0)
	s_barrier
	s_cbranch_scc1 .Lbi_5
	s_mov_b32 s99, 5
	s_branch .Lbs_entry
.Lbs_ret_5:
	s_branch .LBB0_765
.Lbi_5:
	s_cmp_gt_u32 s88, 127
	s_cbranch_scc1 .LBB0_765
	buffer_inv sc1
	s_waitcnt vmcnt(0)

; DI int lane_id() { int l = __builtin_amdgcn_mbcnt_hi(-1, __builtin_amdgcn_mbcnt_lo(-1, 0)); asm volatile("" : "+v"(l)); return l; }
; DI unsigned xb_ld(unsigned* q) { return __hip_atomic_load(q, __ATOMIC_RELAXED, __HIP_MEMORY_SCOPE_AGENT); }
; DI unsigned xb_xcc_id() { return (unsigned)__builtin_amdgcn_s_getreg((3 << 11) | 20) & 0xFu; }
; DI void xcd_barrier_complete(unsigned* bar, unsigned x, unsigned& nloc, unsigned& nx) {
;     const unsigned G = gridDim.x;
;     unsigned sum, cnt, mine, sp = 0u;
;     for (;;) {
;         sum = 0u; cnt = 0u; mine = 0u;
; #pragma unroll
;         for (unsigned j = 0; j < 16; ++j) { const unsigned c = xb_ld(&bar[XB_XCNT(j)]); sum += c; cnt += (c > 0u) ? 1u : 0u; mine = (j == x) ? c : mine; }
; DI void grid_bar(unsigned* bar, volatile LAS unsigned* st, int wid) {
;     ...
;     if (wid == 0) {
;         if (lane_id() == 0) {
;             __builtin_amdgcn_s_waitcnt(0);
;             const unsigned x = xb_xcc_id();
;             unsigned nloc = st[0], nx = st[1];
;             if (nloc == 0u) { xcd_barrier_complete(bar, x, nloc, nx); st[0] = nloc; st[1] = nx; }
.LBB0_805:
	s_cmp_gt_i32 s35, 7
	s_cselect_b64 s[2:3], -1, 0
	s_and_b64 s[4:5], s[8:9], s[2:3]
	s_andn2_b64 vcc, exec, s[4:5]
	s_cbranch_vccnz .LBB0_861
	s_mov_b64 s[8:9], s[0:1]
	s_waitcnt vmcnt(0)
	s_cmp_gt_u32 s88, 63
	s_waitcnt vmcnt(0) lgkmcnt(0)
	s_barrier
	s_cbranch_scc1 .Lbi_6
	s_mov_b32 s99, 6
.Lbs_entry:
	v_mbcnt_hi_u32_b32 v0, -1, v254
	s_nop 0
	v_cmp_eq_u32_e32 vcc, 0, v0
	s_and_saveexec_b64 s[96:97], vcc
	s_cbranch_execz .LBB0_859
	s_add_i32 s11, 0, 0x20000
	v_mov_b32_e32 v0, s11
	s_load_dwordx2 s[8:9], s[8:9], 0xa8
	s_waitcnt vmcnt(0) expcnt(0) lgkmcnt(0)
	s_getreg_b32 s10, hwreg(HW_REG_XCC_ID, 0, 4)
	ds_read_b32 v2, v0
	s_add_i32 s11, 0, 0x20004
	v_mov_b32_e32 v0, s11
	ds_read_b32 v0, v0
	s_and_b32 s54, s10, 15
	s_waitcnt lgkmcnt(1)
	v_cmp_ne_u32_e32 vcc, 0, v2
	s_cbranch_vccnz .LBB0_823
	s_add_u32 s10, s8, 0xcd80200
	s_addc_u32 s11, s9, 0
	s_add_u32 s12, s8, 0xcd80400
	s_addc_u32 s13, s9, 0
	s_add_u32 s14, s8, 0xcd80500
	s_addc_u32 s15, s9, 0
	s_add_u32 s16, s8, 0xcd80600
	s_addc_u32 s17, s9, 0
	s_add_u32 s18, s8, 0xcd80700
	s_addc_u32 s19, s9, 0
	s_add_u32 s20, s8, 0xcd80800
	s_addc_u32 s21, s9, 0
	s_add_u32 s22, s8, 0xcd80900
	s_addc_u32 s23, s9, 0
	s_add_u32 s24, s8, 0xcd80a00
	s_addc_u32 s25, s9, 0
	s_add_u32 s26, s8, 0xcd80b00
	s_addc_u32 s27, s9, 0
	s_add_u32 s28, s8, 0xcd80c00
	s_addc_u32 s29, s9, 0
	s_add_u32 s30, s8, 0xcd80d00
	s_addc_u32 s31, s9, 0
	s_add_u32 s36, s8, 0xcd80e00
	s_addc_u32 s37, s9, 0
	s_add_u32 s38, s8, 0xcd80f00
	s_addc_u32 s39, s9, 0
	s_add_u32 s40, s8, 0xcd81000
	s_addc_u32 s41, s9, 0
	s_add_u32 s42, s8, 0xcd81100
	s_addc_u32 s43, s9, 0
	s_add_u32 s44, s8, 0xcd81200
	s_addc_u32 s45, s9, 0
	s_add_u32 s46, s8, 0xcd81300
	s_addc_u32 s47, s9, 0
	s_mov_b32 s55, 1
	v_mov_b32_e32 v16, 0
	s_branch .LBB0_811

; DI void grid_bar(unsigned* bar, volatile LAS unsigned* st, int wid) {
;     ...
;         }
;     }
;     __syncthreads();
.LBB0_859:
	s_or_b64 exec, exec, s[96:97]
	s_cmp_eq_u32 s99, 0
	s_cbranch_scc1 .Lbs_ret_0
	s_cmp_eq_u32 s99, 1
	s_cbranch_scc1 .Lbs_ret_1
	s_cmp_eq_u32 s99, 2
	s_cbranch_scc1 .Lbs_ret_2
	s_cmp_eq_u32 s99, 3
	s_cbranch_scc1 .Lbs_ret_3
	s_cmp_eq_u32 s99, 4
	s_cbranch_scc1 .Lbs_ret_4
	s_cmp_eq_u32 s99, 5
	s_cbranch_scc1 .Lbs_ret_5
	s_cmp_eq_u32 s99, 7
	s_cbranch_scc1 .Lbs_ret_7
	s_cmp_eq_u32 s99, 8
	s_cbranch_scc1 .Lbs_ret_8
	s_cmp_eq_u32 s99, 9
	s_cbranch_scc1 .Lbs_ret_9
	s_cmp_eq_u32 s99, 10
	s_cbranch_scc1 .Lbs_ret_10
	s_cmp_eq_u32 s99, 11
	s_cbranch_scc1 .Lbs_ret_11
	s_cmp_eq_u32 s99, 12
	s_cbranch_scc1 .Lbs_ret_12
	s_branch .LBB0_860

; #define LAS __attribute__((address_space(3)))
; DI void grid_bar(unsigned* bar, volatile LAS unsigned* st, int wid) {
;     asm volatile("s_waitcnt vmcnt(0)" ::: "memory");
;     __syncthreads();
;     if (wid == 0) {
.Lconv_skip_2:
	s_cmp_gt_i32 s35, 8
	s_cselect_b64 s[2:3], -1, 0
	s_and_b64 s[4:5], s[8:9], s[2:3]
	s_andn2_b64 vcc, exec, s[4:5]
	s_cbranch_vccnz .LBB0_954
	s_mov_b64 s[8:9], s[0:1]
	s_waitcnt vmcnt(0)
	s_cmp_gt_u32 s88, 63
	s_waitcnt vmcnt(0) lgkmcnt(0)
	s_barrier
	s_cbranch_scc1 .Lbi_7
	s_mov_b32 s99, 7
	s_branch .Lbs_entry
.Lbs_ret_7:
	s_branch .LBB0_953
.Lbi_7:
	s_cmp_gt_u32 s88, 127
	s_cbranch_scc1 .LBB0_953
	buffer_inv sc1
	s_waitcnt vmcnt(0)

; #define LAS __attribute__((address_space(3)))
; DI void grid_bar(unsigned* bar, volatile LAS unsigned* st, int wid) {
;     asm volatile("s_waitcnt vmcnt(0)" ::: "memory");
;     __syncthreads();
;     if (wid == 0) {
.Lconv_skip_3:
	s_cmp_gt_i32 s35, 9
	s_cselect_b64 s[4:5], -1, 0
	s_and_b64 s[2:3], s[2:3], s[4:5]
	s_andn2_b64 vcc, exec, s[2:3]
	s_cbranch_vccnz .LBB0_1073
	s_mov_b64 s[8:9], s[0:1]
	s_waitcnt vmcnt(0)
	s_cmp_gt_u32 s88, 63
	s_waitcnt vmcnt(0) lgkmcnt(0)
	s_barrier
	s_cbranch_scc1 .Lbi_8
	s_mov_b32 s99, 8
	s_branch .Lbs_entry
.Lbs_ret_8:
	s_branch .LBB0_1072
.Lbi_8:
	s_cmp_gt_u32 s88, 127
	s_cbranch_scc1 .LBB0_1072
	buffer_inv sc1
	s_waitcnt vmcnt(0)

; #define LAS __attribute__((address_space(3)))
; DI void grid_bar(unsigned* bar, volatile LAS unsigned* st, int wid) {
;     asm volatile("s_waitcnt vmcnt(0)" ::: "memory");
;     __syncthreads();
;     if (wid == 0) {
.LBB0_1101:
	s_cmp_gt_i32 s35, 10
	s_cselect_b64 s[4:5], -1, 0
	s_and_b64 s[2:3], s[2:3], s[4:5]
	s_andn2_b64 vcc, exec, s[2:3]
	s_cbranch_vccnz .LBB0_1157
	s_mov_b64 s[8:9], s[0:1]
	s_waitcnt vmcnt(0)
	s_cmp_gt_u32 s88, 63
	s_waitcnt vmcnt(0) lgkmcnt(0)
	s_barrier
	s_cbranch_scc1 .Lbi_9
	s_mov_b32 s99, 9
	s_branch .Lbs_entry
.Lbs_ret_9:
	s_branch .LBB0_1156
.Lbi_9:
	s_cmp_gt_u32 s88, 127
	s_cbranch_scc1 .LBB0_1156
	buffer_inv sc1
	s_waitcnt vmcnt(0)

; #define LAS __attribute__((address_space(3)))
; DI void grid_bar(unsigned* bar, volatile LAS unsigned* st, int wid) {
;     asm volatile("s_waitcnt vmcnt(0)" ::: "memory");
;     __syncthreads();
;     if (wid == 0) {
.LBB0_1196:
	s_cmp_gt_i32 s35, 11
	s_cselect_b64 s[2:3], -1, 0
	s_and_b64 s[4:5], s[8:9], s[2:3]
	s_andn2_b64 vcc, exec, s[4:5]
	s_cbranch_vccnz .LBB0_1252
	s_mov_b64 s[8:9], s[0:1]
	s_waitcnt vmcnt(0)
	s_cmp_gt_u32 s88, 63
	s_waitcnt vmcnt(0) lgkmcnt(0)
	s_barrier
	s_cbranch_scc1 .Lbi_10
	s_mov_b32 s99, 10
	s_branch .Lbs_entry
.Lbs_ret_10:
	s_branch .LBB0_1251
.Lbi_10:
	s_cmp_gt_u32 s88, 127
	s_cbranch_scc1 .LBB0_1251
	buffer_inv sc1
	s_waitcnt vmcnt(0)

; #define LAS __attribute__((address_space(3)))
; DI void grid_bar(unsigned* bar, volatile LAS unsigned* st, int wid) {
;     asm volatile("s_waitcnt vmcnt(0)" ::: "memory");
;     __syncthreads();
;     if (wid == 0) {
.Lconv_skip_4:
	s_cmp_gt_i32 s35, 12
	s_cselect_b64 s[2:3], -1, 0
	s_and_b64 s[4:5], s[4:5], s[2:3]
	s_andn2_b64 vcc, exec, s[4:5]
	s_cbranch_vccnz .LBB0_1321
	s_mov_b64 s[8:9], s[0:1]
	s_waitcnt vmcnt(0)
	s_cmp_gt_u32 s88, 63
	s_waitcnt vmcnt(0) lgkmcnt(0)
	s_barrier
	s_cbranch_scc1 .Lbi_11
	s_mov_b32 s99, 11
	s_branch .Lbs_entry
.Lbs_ret_11:
	s_branch .LBB0_1320
.Lbi_11:
	s_cmp_gt_u32 s88, 127
	s_cbranch_scc1 .LBB0_1320
	buffer_inv sc1
	s_waitcnt vmcnt(0)

; #define LAS __attribute__((address_space(3)))
; DI void grid_bar(unsigned* bar, volatile LAS unsigned* st, int wid) {
;     asm volatile("s_waitcnt vmcnt(0)" ::: "memory");
;     __syncthreads();
;     if (wid == 0) {
.LBB0_1360:
	s_cmp_gt_i32 s35, 13
	s_cselect_b64 s[2:3], -1, 0
	s_and_b64 s[4:5], s[8:9], s[2:3]
	s_andn2_b64 vcc, exec, s[4:5]
	s_cbranch_vccnz .LBB0_1416
	s_mov_b64 s[8:9], s[0:1]
	s_waitcnt vmcnt(0)
	s_cmp_gt_u32 s88, 63
	s_waitcnt vmcnt(0) lgkmcnt(0)
	s_barrier
	s_cbranch_scc1 .Lbi_12
	s_mov_b32 s99, 12
	s_branch .Lbs_entry
.Lbs_ret_12:
	s_branch .LBB0_1415
.Lbi_12:
	s_cmp_gt_u32 s88, 127
	s_cbranch_scc1 .LBB0_1415
	buffer_inv sc1
	s_waitcnt vmcnt(0)
